# hyena short-conv loop: next item's loads stay in flight during compute (counted vmcnt), on top of norm / filter-tail / MFMA-order edits
# speedup vs baseline: 1.0269x; 1.0102x over previous
.LBB0_842:
	s_or_b64 exec, exec, s[6:7]
	s_add_u32 s12, s26, 0x22100000
	s_addc_u32 s13, s27, 0
	s_add_u32 s14, s26, 0x1d100000
	s_addc_u32 s15, s27, 0
	s_add_i32 s6, s2, s42
	v_mul_u32_u24_e32 v230, 0x104, v226
	v_mul_u32_u24_e32 v231, 0x820, v201
	s_lshl_b32 s47, s42, 2
	s_lshl_b32 s50, s6, 6
	s_lshl_b32 s51, s42, 6
	s_mov_b32 s68, -1
	s_movk_i32 s60, 0x1800
	v_mov_b32_e32 v14, 0
	s_movk_i32 s61, 0x2000
	s_mov_b64 s[16:17], 0x3000
	s_mov_b64 s[20:21], 0x6000
	s_mov_b64 s[26:27], 0x1000
	s_mov_b64 s[28:29], 0x4000
	s_movk_i32 s62, 0x4000
	s_mov_b64 s[30:31], 0x7000
	s_movk_i32 s63, 0x7000
	s_mov_b64 s[36:37], 0x2000
	s_mov_b64 s[38:39], 0x5000
	s_movk_i32 s64, 0x5000
	s_mov_b64 s[54:55], 0x8000
	s_mov_b32 s65, 0x8000
	s_mov_b32 s66, 0xffff0000
	s_movk_i32 s67, 0x7fff
	s_mov_b32 s34, s2
	s_waitcnt vmcnt(0)
	s_branch .LBB0_845
.LBB0_843:
	v_lshlrev_b32_e32 v16, 2, v15
	v_mov_b32_e32 v17, v14
	s_waitcnt vmcnt(15)
	v_lshl_add_u64 v[154:155], s[22:23], 0, v[16:17]
	v_add_co_u32_e32 v82, vcc, s62, v154
	v_lshl_add_u64 v[106:107], s[18:19], 0, v[16:17]
	global_load_dwordx4 v[86:89], v16, s[18:19] offset:16
	global_load_dwordx4 v[66:69], v16, s[18:19]
	global_load_dwordx4 v[98:101], v16, s[22:23] offset:16
	global_load_dwordx4 v[70:73], v16, s[22:23]
	v_lshl_add_u64 v[16:17], v[154:155], 0, s[16:17]
	v_addc_co_u32_e32 v83, vcc, 0, v155, vcc
	global_load_dwordx4 v[90:93], v[82:83], off offset:-4096
	v_lshl_add_u64 v[84:85], v[154:155], 0, s[20:21]
	global_load_dwordx4 v[122:125], v[16:17], off offset:16
	global_load_dwordx4 v[142:145], v[84:85], off offset:16
	v_add_co_u32_e32 v16, vcc, s63, v154
	v_lshl_add_u64 v[84:85], v[106:107], 0, s[26:27]
	s_nop 0
	v_addc_co_u32_e32 v17, vcc, 0, v155, vcc
	v_add_co_u32_e32 v108, vcc, s61, v106
	v_lshl_add_u64 v[94:95], v[154:155], 0, s[26:27]
	s_nop 0
	v_addc_co_u32_e32 v109, vcc, 0, v107, vcc
	v_add_co_u32_e32 v118, vcc, s61, v154
	v_lshl_add_u64 v[96:97], v[154:155], 0, s[28:29]
	s_nop 0
	v_addc_co_u32_e32 v119, vcc, 0, v155, vcc
	global_load_dwordx4 v[110:113], v[16:17], off offset:-4096
	global_load_dwordx4 v[102:105], v[84:85], off offset:16
	s_nop 0
	global_load_dwordx4 v[82:85], v[82:83], off
	s_nop 0
	global_load_dwordx4 v[130:133], v[94:95], off offset:16
	global_load_dwordx4 v[138:141], v[96:97], off offset:16
	v_lshl_add_u64 v[114:115], v[154:155], 0, s[30:31]
	global_load_dwordx4 v[94:97], v[16:17], off
	global_load_dwordx4 v[146:149], v[114:115], off offset:16
	v_lshl_add_u64 v[16:17], v[106:107], 0, s[36:37]
	s_waitcnt vmcnt(26)
	v_add_co_u32_e32 v158, vcc, s64, v154
	global_load_dwordx4 v[114:117], v[108:109], off offset:-4096
	s_nop 0
	global_load_dwordx4 v[106:109], v[108:109], off
	s_nop 0
	global_load_dwordx4 v[150:153], v[16:17], off offset:16
	v_lshl_add_u64 v[16:17], v[154:155], 0, s[36:37]
	v_addc_co_u32_e32 v159, vcc, 0, v155, vcc
	global_load_dwordx4 v[134:137], v[118:119], off offset:-4096
	s_nop 0
	global_load_dwordx4 v[118:121], v[118:119], off
	v_lshl_add_u64 v[156:157], v[154:155], 0, s[38:39]
	global_load_dwordx4 v[162:165], v[16:17], off offset:16
	global_load_dwordx4 v[166:169], v[156:157], off offset:16
	v_lshl_add_u64 v[16:17], v[154:155], 0, s[54:55]
	v_add_co_u32_e32 v154, vcc, s65, v154
	s_mov_b32 s68, s6
	s_nop 0
	v_addc_co_u32_e32 v155, vcc, 0, v155, vcc
	global_load_dwordx4 v[154:157], v[154:155], off
	s_nop 0
	global_load_dwordx4 v[158:161], v[158:159], off
	s_nop 0
	global_load_dwordx4 v[170:173], v[16:17], off offset:16
	s_waitcnt vmcnt(23)
	v_mov_b32_e32 v16, v87
	v_mov_b32_e32 v17, v89
	s_waitcnt vmcnt(21)
	v_mov_b32_e32 v184, v99
	v_mov_b32_e32 v185, v101
	v_mov_b32_e32 v190, v86
	v_mov_b32_e32 v191, v88
	v_mov_b32_e32 v192, v98
	v_mov_b32_e32 v193, v100
	v_mov_b32_e32 v202, v67
	v_mov_b32_e32 v203, v69
	s_waitcnt vmcnt(20)
	v_mov_b32_e32 v204, v71
	v_mov_b32_e32 v205, v73
	s_waitcnt vmcnt(18)
	v_mov_b32_e32 v188, v123
	v_mov_b32_e32 v189, v125
	s_waitcnt vmcnt(17)
	v_mov_b32_e32 v186, v143
	v_mov_b32_e32 v187, v145
	v_mov_b32_e32 v196, v122
	v_mov_b32_e32 v197, v124
	v_mov_b32_e32 v194, v142
	v_mov_b32_e32 v195, v144
	v_mov_b32_e32 v208, v91
	v_mov_b32_e32 v209, v93
	v_mov_b32_e32 v214, v66
	v_mov_b32_e32 v215, v68
	v_mov_b32_e32 v216, v70
	s_waitcnt vmcnt(16)
	v_mov_b32_e32 v206, v111
	v_mov_b32_e32 v207, v113
	v_mov_b32_e32 v217, v72
	v_mov_b32_e32 v212, v90
	v_mov_b32_e32 v213, v92
	v_mov_b32_e32 v210, v110
	v_mov_b32_e32 v211, v112
	v_mov_b32_e32 v176, v110
	v_mov_b32_e32 v177, v112
	v_mov_b32_e32 v178, v90
	v_mov_b32_e32 v179, v92
	v_mov_b32_e32 v180, v70
	v_mov_b32_e32 v181, v72
	v_mov_b32_e32 v182, v66
	v_mov_b32_e32 v183, v68
	v_mov_b32_e32 v112, v111
	v_mov_b32_e32 v92, v91
	v_mov_b32_e32 v72, v71
	v_mov_b32_e32 v68, v67
	v_mov_b32_e32 v66, v142
	v_mov_b32_e32 v67, v144
	v_mov_b32_e32 v70, v122
	v_mov_b32_e32 v71, v124
	v_mov_b32_e32 v90, v98
	v_mov_b32_e32 v91, v100
	v_mov_b32_e32 v110, v86
	v_mov_b32_e32 v111, v88
	v_mov_b32_e32 v144, v143
	v_mov_b32_e32 v124, v123
	v_mov_b32_e32 v100, v99
	v_mov_b32_e32 v88, v87
	s_waitcnt vmcnt(0)
.LBB0_844:
	s_mul_i32 s8, s44, 0x4100
	s_add_i32 s8, s8, 16
	v_lshlrev_b32_e32 v86, 2, v227
	v_add3_u32 v142, s8, v230, v86
	v_and_b32_e32 v87, 0xffff0000, v30
	v_lshlrev_b32_e32 v86, 16, v30
	v_pk_fma_f32 v[86:87], v[134:135], v[86:87], v[114:115]
	v_and_b32_e32 v99, 0xffff0000, v22
	v_lshlrev_b32_e32 v98, 16, v22
	v_pk_fma_f32 v[86:87], v[82:83], v[98:99], v[86:87]
	v_and_b32_e32 v99, 0xffff0000, v26
	v_lshlrev_b32_e32 v98, 16, v26
	v_pk_fma_f32 v[86:87], v[94:95], v[98:99], v[86:87]
	v_and_b32_e32 v99, 0xffff0000, v46
	v_lshlrev_b32_e32 v98, 16, v46
	v_pk_fma_f32 v[98:99], v[118:119], v[98:99], v[106:107]
	v_and_b32_e32 v123, 0xffff0000, v42
	v_lshlrev_b32_e32 v122, 16, v42
	v_pk_fma_f32 v[98:99], v[158:159], v[122:123], v[98:99]
	v_and_b32_e32 v123, 0xffff0000, v50
	v_lshlrev_b32_e32 v122, 16, v50
	v_pk_fma_f32 v[98:99], v[154:155], v[122:123], v[98:99]
	v_lshlrev_b32_e32 v26, 16, v47
	v_pk_mul_f32 v[86:87], v[98:99], v[86:87]
	ds_write2_b32 v142, v86, v87 offset1:1
	v_and_b32_e32 v87, 0xffff0000, v31
	v_lshlrev_b32_e32 v86, 16, v31
	v_pk_fma_f32 v[30:31], v[136:137], v[86:87], v[116:117]
	v_and_b32_e32 v87, 0xffff0000, v23
	v_lshlrev_b32_e32 v86, 16, v23
	v_pk_fma_f32 v[22:23], v[84:85], v[86:87], v[30:31]
	v_and_b32_e32 v31, 0xffff0000, v27
	v_lshlrev_b32_e32 v30, 16, v27
	v_and_b32_e32 v27, 0xffff0000, v47
	v_pk_fma_f32 v[22:23], v[96:97], v[30:31], v[22:23]
	v_pk_fma_f32 v[26:27], v[120:121], v[26:27], v[108:109]
	v_and_b32_e32 v31, 0xffff0000, v43
	v_lshlrev_b32_e32 v30, 16, v43
	v_pk_fma_f32 v[26:27], v[160:161], v[30:31], v[26:27]
	v_and_b32_e32 v31, 0xffff0000, v51
	v_lshlrev_b32_e32 v30, 16, v51
	v_pk_fma_f32 v[26:27], v[156:157], v[30:31], v[26:27]
	s_and_b32 s6, s3, 0xffffffc0
	v_pk_mul_f32 v[22:23], v[26:27], v[22:23]
	ds_write2_b32 v142, v22, v23 offset0:2 offset1:3
	v_lshlrev_b32_e32 v23, 16, v11
	v_lshlrev_b32_e32 v22, 16, v10
	v_and_b32_e32 v11, 0xffff0000, v11
	v_and_b32_e32 v10, 0xffff0000, v10
	v_pk_fma_f32 v[22:23], v[216:217], v[22:23], v[214:215]
	v_lshlrev_b32_e32 v27, 16, v7
	v_lshlrev_b32_e32 v26, 16, v6
	v_pk_fma_f32 v[10:11], v[204:205], v[10:11], v[202:203]
	v_and_b32_e32 v7, 0xffff0000, v7
	v_and_b32_e32 v6, 0xffff0000, v6
	v_pk_fma_f32 v[22:23], v[212:213], v[26:27], v[22:23]
	v_lshlrev_b32_e32 v27, 16, v3
	v_lshlrev_b32_e32 v26, 16, v2
	v_pk_fma_f32 v[6:7], v[208:209], v[6:7], v[10:11]
	v_and_b32_e32 v3, 0xffff0000, v3
	v_and_b32_e32 v2, 0xffff0000, v2
	v_pk_fma_f32 v[2:3], v[206:207], v[2:3], v[6:7]
	v_and_b32_e32 v7, 0xffff0000, v32
	v_lshlrev_b32_e32 v6, 16, v32
	v_pk_fma_f32 v[6:7], v[130:131], v[6:7], v[102:103]
	v_and_b32_e32 v11, 0xffff0000, v24
	v_lshlrev_b32_e32 v10, 16, v24
	v_pk_fma_f32 v[6:7], v[138:139], v[10:11], v[6:7]
	v_and_b32_e32 v11, 0xffff0000, v28
	v_lshlrev_b32_e32 v10, 16, v28
	v_pk_fma_f32 v[6:7], v[146:147], v[10:11], v[6:7]
	v_and_b32_e32 v11, 0xffff0000, v48
	v_lshlrev_b32_e32 v10, 16, v48
	v_pk_fma_f32 v[22:23], v[210:211], v[26:27], v[22:23]
	v_pk_fma_f32 v[10:11], v[162:163], v[10:11], v[150:151]
	v_and_b32_e32 v27, 0xffff0000, v44
	v_lshlrev_b32_e32 v26, 16, v44
	v_pk_fma_f32 v[10:11], v[166:167], v[26:27], v[10:11]
	v_and_b32_e32 v27, 0xffff0000, v52
	v_lshlrev_b32_e32 v26, 16, v52
	v_pk_fma_f32 v[10:11], v[170:171], v[26:27], v[10:11]
	v_lshlrev_b32_e32 v24, 16, v45
	v_pk_mul_f32 v[6:7], v[10:11], v[6:7]
	ds_write2_b32 v142, v6, v7 offset0:4 offset1:5
	v_and_b32_e32 v7, 0xffff0000, v33
	v_lshlrev_b32_e32 v6, 16, v33
	v_pk_fma_f32 v[6:7], v[132:133], v[6:7], v[104:105]
	v_and_b32_e32 v11, 0xffff0000, v25
	v_lshlrev_b32_e32 v10, 16, v25
	v_pk_fma_f32 v[6:7], v[140:141], v[10:11], v[6:7]
	v_and_b32_e32 v11, 0xffff0000, v29
	v_lshlrev_b32_e32 v10, 16, v29
	v_pk_fma_f32 v[6:7], v[148:149], v[10:11], v[6:7]
	v_and_b32_e32 v11, 0xffff0000, v49
	v_lshlrev_b32_e32 v10, 16, v49
	v_pk_fma_f32 v[10:11], v[164:165], v[10:11], v[152:153]
	v_and_b32_e32 v25, 0xffff0000, v45
	v_pk_fma_f32 v[10:11], v[168:169], v[24:25], v[10:11]
	v_and_b32_e32 v25, 0xffff0000, v53
	v_lshlrev_b32_e32 v24, 16, v53
	v_pk_fma_f32 v[10:11], v[172:173], v[24:25], v[10:11]
	v_mov_b32_e32 v175, v14
	v_pk_mul_f32 v[6:7], v[10:11], v[6:7]
	ds_write2_b32 v142, v6, v7 offset0:6 offset1:7
	v_lshlrev_b32_e32 v7, 16, v13
	v_lshlrev_b32_e32 v6, 16, v12
	v_pk_fma_f32 v[6:7], v[192:193], v[6:7], v[190:191]
	v_lshlrev_b32_e32 v11, 16, v9
	v_lshlrev_b32_e32 v10, 16, v8
	v_pk_fma_f32 v[6:7], v[196:197], v[10:11], v[6:7]
	v_lshlrev_b32_e32 v11, 16, v5
	v_lshlrev_b32_e32 v10, 16, v4
	v_pk_fma_f32 v[6:7], v[194:195], v[10:11], v[6:7]
	v_and_b32_e32 v11, 0xffff0000, v13
	v_and_b32_e32 v10, 0xffff0000, v12
	v_pk_fma_f32 v[10:11], v[184:185], v[10:11], v[16:17]
	v_and_b32_e32 v9, 0xffff0000, v9
	v_and_b32_e32 v8, 0xffff0000, v8
	v_pk_fma_f32 v[8:9], v[188:189], v[8:9], v[10:11]
	v_and_b32_e32 v5, 0xffff0000, v5
	v_and_b32_e32 v4, 0xffff0000, v4
	v_pk_fma_f32 v[4:5], v[186:187], v[4:5], v[8:9]
	v_bfe_u32 v9, v22, 16, 1
	v_bfe_u32 v11, v6, 16, 1
	v_bfe_u32 v12, v7, 16, 1
	v_add3_u32 v9, v22, v9, s67
	v_bfe_u32 v16, v2, 16, 1
	v_add_u32_e32 v8, s6, v226
	v_add3_u32 v7, v7, v12, s67
	v_add3_u32 v6, v6, v11, s67
	v_lshrrev_b32_e32 v9, 16, v9
	v_bfe_u32 v11, v5, 16, 1
	v_bfe_u32 v12, v4, 16, 1
	v_add3_u32 v2, v2, v16, s67
	v_bfe_u32 v10, v23, 16, 1
	v_lshrrev_b32_e32 v6, 16, v6
	v_lshrrev_b32_e32 v7, 16, v7
	v_add3_u32 v4, v4, v12, s67
	v_add3_u32 v5, v5, v11, s67
	v_and_or_b32 v2, v2, s66, v9
	v_ashrrev_i32_e32 v9, 31, v8
	v_add3_u32 v10, v23, v10, s67
	v_bfe_u32 v13, v3, 16, 1
	v_and_or_b32 v5, v5, s66, v7
	v_and_or_b32 v4, v4, s66, v6
	v_lshlrev_b64 v[6:7], 11, v[8:9]
	v_lshrrev_b32_e32 v10, 16, v10
	v_add3_u32 v3, v3, v13, s67
	v_lshl_add_u64 v[6:7], s[12:13], 0, v[6:7]
	v_lshlrev_b32_e32 v8, 1, v15
	v_mov_b32_e32 v9, v14
	v_and_or_b32 v3, v3, s66, v10
	v_lshl_add_u64 v[6:7], v[6:7], 0, v[8:9]
	global_store_dwordx4 v[6:7], v[2:5], off
	s_waitcnt lgkmcnt(0)
	s_barrier
	v_lshlrev_b32_e32 v2, 2, v226
	v_add3_u32 v6, s8, v231, v2
	ds_read2_b32 v[2:3], v6 offset1:65
	s_waitcnt vmcnt(1)
	v_mov_b64_e32 v[46:47], v[78:79]
	v_mov_b64_e32 v[30:31], v[58:59]
	v_mov_b64_e32 v[10:11], v[34:35]
	v_mov_b64_e32 v[42:43], v[74:75]
	s_waitcnt lgkmcnt(0)
	v_bfe_u32 v4, v2, 16, 1
	v_add3_u32 v2, v2, v4, s67
	ds_read2_b32 v[4:5], v6 offset0:130 offset1:195
	v_bfe_u32 v7, v3, 16, 1
	v_lshrrev_b32_e32 v2, 16, v2
	v_add3_u32 v3, v3, v7, s67
	v_and_or_b32 v2, v3, s66, v2
	s_waitcnt lgkmcnt(0)
	v_bfe_u32 v3, v4, 16, 1
	v_add3_u32 v3, v4, v3, s67
	v_add_u32_e32 v4, 0x400, v6
	ds_read2_b32 v[6:7], v4 offset0:4 offset1:69
	v_bfe_u32 v8, v5, 16, 1
	v_lshrrev_b32_e32 v3, 16, v3
	v_add3_u32 v5, v5, v8, s67
	ds_read2_b32 v[8:9], v4 offset0:134 offset1:199
	v_and_or_b32 v3, v5, s66, v3
	s_waitcnt lgkmcnt(1)
	v_bfe_u32 v5, v6, 16, 1
	v_add3_u32 v5, v6, v5, s67
	v_lshrrev_b32_e32 v4, 16, v5
	v_bfe_u32 v5, v7, 16, 1
	v_add3_u32 v5, v7, v5, s67
	v_and_or_b32 v4, v5, s66, v4
	s_waitcnt lgkmcnt(0)
	v_bfe_u32 v5, v8, 16, 1
	v_add3_u32 v5, v8, v5, s67
	v_bfe_u32 v6, v9, 16, 1
	v_lshrrev_b32_e32 v5, 16, v5
	v_add3_u32 v6, v9, v6, s67
	v_and_or_b32 v5, v6, s66, v5
	v_add_u32_e32 v6, s7, v226
	v_mul_u32_u24_e32 v6, 0x5000, v6
	v_lshlrev_b32_e32 v6, 1, v6
	v_mov_b32_e32 v7, v14
	v_lshl_add_u64 v[6:7], s[14:15], 0, v[6:7]
	s_ashr_i32 s7, s6, 31
	v_lshl_add_u64 v[6:7], s[6:7], 1, v[6:7]
	v_lshl_add_u64 v[6:7], v[6:7], 0, v[174:175]
	global_store_dwordx4 v[6:7], v[2:5], off
	v_mov_b64_e32 v[22:23], v[54:55]
	v_mov_b64_e32 v[6:7], v[18:19]
	v_mov_b64_e32 v[26:27], v[62:63]
	v_mov_b64_e32 v[2:3], v[38:39]
	s_xor_b32 s44, s44, 1
	s_add_i32 s3, s3, s47
	s_add_i32 s50, s50, s51
	s_andn2_b64 vcc, exec, s[56:57]
	v_mov_b64_e32 v[48:49], v[80:81]
	v_mov_b64_e32 v[32:33], v[60:61]
	v_mov_b64_e32 v[12:13], v[36:37]
	v_mov_b64_e32 v[44:45], v[76:77]
	v_mov_b64_e32 v[24:25], v[56:57]
	v_mov_b64_e32 v[8:9], v[20:21]
	v_mov_b64_e32 v[28:29], v[64:65]
	v_mov_b64_e32 v[4:5], v[40:41]
	s_mov_b32 s34, s69
	v_mov_b32_e32 v50, v126
	v_mov_b32_e32 v51, v127
	v_mov_b32_e32 v52, v128
	v_mov_b32_e32 v53, v129
	s_cbranch_vccz .LBB0_861
